# attn_combine: nt hint on the read-once partial-output loads
# speedup vs baseline: 1.0013x; 1.0013x over previous
; __device__ __forceinline__ bf16* po_base(unsigned char* ws, int pat) { return (bf16*)(ws + (pat < 2 ? 436 * MiB + (size_t)pat * 32 * MiB : WS_Y)); }
; __device__ __forceinline__ void attn_combine(unsigned char* ws, const float* __restrict__ PM, bf16* CAT, int gtid, int gthreads, int iend = S * 128) {
;     for (int idx = gtid; idx < iend; idx += gthreads) {
;         const int t = idx >> 7, c = (idx & 127) * 8, hh = c >> 7;
;         float mm[3], ll[3];
; #pragma unroll
;         for (int p = 0; p < 3; ++p) { const f32x2_t ml = *(const f32x2_t*)(PM + (((size_t)p * S + t) * 8 + hh) * 2); mm[p] = ml[0]; ll[p] = ml[1]; }
;         const float ma = fmaxf(mm[0], fmaxf(mm[1], mm[2]));
;         float w[3], den = 0.f;
; #pragma unroll
;         for (int p = 0; p < 3; ++p) { w[p] = exp2f(mm[p] - ma) * ll[p]; den += w[p]; }
;         const float inv = 1.f / den;
;         float o[8] = {0.f, 0.f, 0.f, 0.f, 0.f, 0.f, 0.f, 0.f};
; #pragma unroll
;         for (int p = 0; p < 3; ++p) {
;             const u32x4 v = *(const u32x4*)(po_base(ws, p) + (size_t)t * 1024 + c); const float wp = w[p] * inv;
.Lcmb_split:
	s_lshl_b32 s4, s4, 14
	s_lshl_b32 s18, s18, 14
	s_mul_hi_u32 s4, s4, 0xcccccccd
	s_lshr_b32 s4, s4, 2
	s_mul_hi_u32 s18, s18, 0xcccccccd
	s_lshr_b32 s18, s18, 2
	v_add_u32_e32 v2, s4, v186
	v_readlane_b32 s26, v245, 38
	v_readlane_b32 s27, v245, 39
	s_add_u32 s6, s88, 0x600000
	s_addc_u32 s7, s89, 0
	s_add_u32 s8, s88, 0x700000
	s_addc_u32 s9, s89, 0
	s_add_u32 s16, s88, 0x1b400000
	s_addc_u32 s17, s89, 0
	s_add_u32 s20, s88, 0x1d400000
	s_addc_u32 s21, s89, 0
	v_readlane_b32 s22, v245, 15
	v_readlane_b32 s23, v245, 16
	s_sub_i32 s0, s18, s4
	s_add_i32 s0, s0, 2047
	s_lshr_b32 s0, s0, 11
	s_add_i32 s1, s18, -1
	s_mov_b32 s19, 0xc2fc0000
	v_mov_b32_e32 v1, 0
	v_mov_b32_e32 v4, 0x42800000
	v_not_b32_e32 v5, 63
	v_min_i32_e32 v60, s1, v2
	v_ashrrev_i32_e32 v59, 7, v60
	v_lshrrev_b32_e32 v61, 1, v60
	v_and_b32_e32 v61, 56, v61
	v_lshl_or_b32 v61, v59, 6, v61
	global_load_dwordx2 v[40:41], v61, s[26:27]
	global_load_dwordx2 v[42:43], v61, s[6:7]
	global_load_dwordx2 v[44:45], v61, s[8:9]
	v_and_b32_e32 v58, 0x7f, v60
	v_lshlrev_b32_e32 v60, 4, v60
	v_lshlrev_b32_e32 v58, 4, v58
	global_load_dwordx4 v[46:49], v60, s[16:17] nt
	v_lshl_or_b32 v58, v59, 12, v58
	global_load_dwordx4 v[50:53], v60, s[20:21] nt
	global_load_dwordx4 v[54:57], v60, s[22:23] nt
	v_add_u32_e32 v84, 512, v2
	v_min_i32_e32 v84, s1, v84
	v_ashrrev_i32_e32 v83, 7, v84
	v_lshrrev_b32_e32 v85, 1, v84
	v_and_b32_e32 v85, 56, v85
	v_lshl_or_b32 v85, v83, 6, v85
	global_load_dwordx2 v[64:65], v85, s[26:27]
	global_load_dwordx2 v[66:67], v85, s[6:7]
	global_load_dwordx2 v[68:69], v85, s[8:9]
	v_and_b32_e32 v82, 0x7f, v84
	v_lshlrev_b32_e32 v84, 4, v84
	v_lshlrev_b32_e32 v82, 4, v82
	global_load_dwordx4 v[70:73], v84, s[16:17] nt
	v_lshl_or_b32 v82, v83, 12, v82
	global_load_dwordx4 v[74:77], v84, s[20:21] nt
	global_load_dwordx4 v[78:81], v84, s[22:23] nt
	v_add_u32_e32 v108, 1024, v2
	v_min_i32_e32 v108, s1, v108
	v_ashrrev_i32_e32 v107, 7, v108
	v_lshrrev_b32_e32 v109, 1, v108
	v_and_b32_e32 v109, 56, v109
	v_lshl_or_b32 v109, v107, 6, v109
	global_load_dwordx2 v[88:89], v109, s[26:27]
	global_load_dwordx2 v[90:91], v109, s[6:7]
	global_load_dwordx2 v[92:93], v109, s[8:9]
	v_and_b32_e32 v106, 0x7f, v108
	v_lshlrev_b32_e32 v108, 4, v108
	v_lshlrev_b32_e32 v106, 4, v106
	global_load_dwordx4 v[94:97], v108, s[16:17] nt
	v_lshl_or_b32 v106, v107, 12, v106
	global_load_dwordx4 v[98:101], v108, s[20:21] nt
	global_load_dwordx4 v[102:105], v108, s[22:23] nt
	v_add_u32_e32 v132, 1536, v2
	v_min_i32_e32 v132, s1, v132
	v_ashrrev_i32_e32 v131, 7, v132
	v_lshrrev_b32_e32 v133, 1, v132
	v_and_b32_e32 v133, 56, v133
	v_lshl_or_b32 v133, v131, 6, v133
	global_load_dwordx2 v[112:113], v133, s[26:27]
	global_load_dwordx2 v[114:115], v133, s[6:7]
	global_load_dwordx2 v[116:117], v133, s[8:9]
	v_and_b32_e32 v130, 0x7f, v132
	v_lshlrev_b32_e32 v132, 4, v132
	v_lshlrev_b32_e32 v130, 4, v130
	global_load_dwordx4 v[118:121], v132, s[16:17] nt
	v_lshl_or_b32 v130, v131, 12, v130
	global_load_dwordx4 v[122:125], v132, s[20:21] nt
	global_load_dwordx4 v[126:129], v132, s[22:23] nt
	v_add_u32_e32 v2, 2048, v2
.Lcmb_loop:
	s_cmp_eq_u32 s0, 1
	s_cbranch_scc1 .Lcmb_lastA
	v_min_i32_e32 v156, s1, v2
	v_ashrrev_i32_e32 v155, 7, v156
	v_lshrrev_b32_e32 v157, 1, v156
	v_and_b32_e32 v157, 56, v157
	v_lshl_or_b32 v157, v155, 6, v157
	global_load_dwordx2 v[136:137], v157, s[26:27]
	global_load_dwordx2 v[138:139], v157, s[6:7]
	global_load_dwordx2 v[140:141], v157, s[8:9]
	v_and_b32_e32 v154, 0x7f, v156
	v_lshlrev_b32_e32 v156, 4, v156
	v_lshlrev_b32_e32 v154, 4, v154
	global_load_dwordx4 v[142:145], v156, s[16:17] nt
	v_lshl_or_b32 v154, v155, 12, v154
	global_load_dwordx4 v[146:149], v156, s[20:21] nt
	global_load_dwordx4 v[150:153], v156, s[22:23] nt
	v_add_u32_e32 v180, 512, v2
	v_min_i32_e32 v180, s1, v180
	v_ashrrev_i32_e32 v179, 7, v180
	v_lshrrev_b32_e32 v181, 1, v180
	v_and_b32_e32 v181, 56, v181
	v_lshl_or_b32 v181, v179, 6, v181
	global_load_dwordx2 v[160:161], v181, s[26:27]
	global_load_dwordx2 v[162:163], v181, s[6:7]
	global_load_dwordx2 v[164:165], v181, s[8:9]
	v_and_b32_e32 v178, 0x7f, v180
	v_lshlrev_b32_e32 v180, 4, v180
	v_lshlrev_b32_e32 v178, 4, v178
	global_load_dwordx4 v[166:169], v180, s[16:17] nt
	v_lshl_or_b32 v178, v179, 12, v178
	global_load_dwordx4 v[170:173], v180, s[20:21] nt
	global_load_dwordx4 v[174:177], v180, s[22:23] nt
	v_add_u32_e32 v208, 1024, v2
	v_min_i32_e32 v208, s1, v208
	v_ashrrev_i32_e32 v207, 7, v208
	v_lshrrev_b32_e32 v209, 1, v208
	v_and_b32_e32 v209, 56, v209
	v_lshl_or_b32 v209, v207, 6, v209
	global_load_dwordx2 v[188:189], v209, s[26:27]
	global_load_dwordx2 v[190:191], v209, s[6:7]
	global_load_dwordx2 v[192:193], v209, s[8:9]
	v_and_b32_e32 v206, 0x7f, v208
	v_lshlrev_b32_e32 v208, 4, v208
	v_lshlrev_b32_e32 v206, 4, v206
	global_load_dwordx4 v[194:197], v208, s[16:17] nt
	v_lshl_or_b32 v206, v207, 12, v206
	global_load_dwordx4 v[198:201], v208, s[20:21] nt
	global_load_dwordx4 v[202:205], v208, s[22:23] nt
	v_add_u32_e32 v232, 1536, v2
	v_min_i32_e32 v232, s1, v232
	v_ashrrev_i32_e32 v231, 7, v232
	v_lshrrev_b32_e32 v233, 1, v232
	v_and_b32_e32 v233, 56, v233
	v_lshl_or_b32 v233, v231, 6, v233
	global_load_dwordx2 v[212:213], v233, s[26:27]
	global_load_dwordx2 v[214:215], v233, s[6:7]
	global_load_dwordx2 v[216:217], v233, s[8:9]
	v_and_b32_e32 v230, 0x7f, v232
	v_lshlrev_b32_e32 v232, 4, v232
	v_lshlrev_b32_e32 v230, 4, v230
	global_load_dwordx4 v[218:221], v232, s[16:17] nt
	v_lshl_or_b32 v230, v231, 12, v230
	global_load_dwordx4 v[222:225], v232, s[20:21] nt
	global_load_dwordx4 v[226:229], v232, s[22:23] nt
	v_add_u32_e32 v2, 2048, v2
	s_waitcnt vmcnt(42)
; __device__ __forceinline__ unsigned pk2(float lo, float hi) { f32x2_t v = {lo, hi}; bf16x2_t b = __builtin_convertvector(v, bf16x2_t); return __builtin_bit_cast(unsigned, b); }
; __device__ __forceinline__ float bflo(unsigned w) { return __uint_as_float(w << 16); }
; __device__ __forceinline__ float bfhi(unsigned w) { return __uint_as_float(w & 0xffff0000u); }
; __device__ __forceinline__ bf16* po_base(unsigned char* ws, int pat) { return (bf16*)(ws + (pat < 2 ? 436 * MiB + (size_t)pat * 32 * MiB : WS_Y)); }
; __device__ __forceinline__ void attn_combine(unsigned char* ws, const float* __restrict__ PM, bf16* CAT, int gtid, int gthreads, int iend = S * 128) {
;     ...
;         for (int p = 0; p < 3; ++p) { const f32x2_t ml = *(const f32x2_t*)(PM + (((size_t)p * S + t) * 8 + hh) * 2); mm[p] = ml[0]; ll[p] = ml[1]; }
;         const float ma = fmaxf(mm[0], fmaxf(mm[1], mm[2]));
;         float w[3], den = 0.f;
; #pragma unroll
;         for (int p = 0; p < 3; ++p) { w[p] = exp2f(mm[p] - ma) * ll[p]; den += w[p]; }
;         const float inv = 1.f / den;
;         float o[8] = {0.f, 0.f, 0.f, 0.f, 0.f, 0.f, 0.f, 0.f};
; #pragma unroll
;         for (int p = 0; p < 3; ++p) {
;             const u32x4 v = *(const u32x4*)(po_base(ws, p) + (size_t)t * 1024 + c); const float wp = w[p] * inv;
;             o[0] += wp * bflo(v.x); o[1] += wp * bfhi(v.x); o[2] += wp * bflo(v.y); o[3] += wp * bfhi(v.y); o[4] += wp * bflo(v.z); o[5] += wp * bfhi(v.z); o[6] += wp * bflo(v.w); o[7] += wp * bfhi(v.w);
;         }
;         u32x4 ov; ov.x = pk2(o[0], o[1]); ov.y = pk2(o[2], o[3]); ov.z = pk2(o[4], o[5]); ov.w = pk2(o[6], o[7]);
;         *(u32x4*)(CAT + (size_t)t * 2048 + c) = ov;
	v_max3_f32 v0, v40, v42, v44
	v_sub_f32_e32 v18, v40, v0
	v_sub_f32_e32 v36, v42, v0
	v_sub_f32_e32 v0, v44, v0
	v_cmp_gt_f32_e32 vcc, s19, v18
	v_cmp_gt_f32_e64 s[4:5], s19, v36
	v_cmp_gt_f32_e64 s[32:33], s19, v0
	v_cndmask_b32_e32 v37, 0, v4, vcc
	v_cndmask_b32_e64 v38, 0, v4, s[4:5]
	v_cndmask_b32_e64 v39, 0, v4, s[32:33]
	v_add_f32_e32 v18, v18, v37
	v_add_f32_e32 v36, v36, v38
	v_add_f32_e32 v0, v0, v39
	v_exp_f32_e32 v18, v18
	v_exp_f32_e32 v36, v36
	v_exp_f32_e32 v0, v0
	v_cndmask_b32_e32 v37, 0, v5, vcc
	v_cndmask_b32_e64 v38, 0, v5, s[4:5]
	v_cndmask_b32_e64 v39, 0, v5, s[32:33]
	v_mov_b32_e32 v20, v45
	v_mov_b32_e32 v21, v43
	v_ldexp_f32 v18, v18, v37
	v_ldexp_f32 v37, v36, v38
	v_ldexp_f32 v36, v0, v39
	v_mul_f32_e32 v0, v41, v18
	v_fma_f32 v38, v41, v18, 0
	v_pk_mul_f32 v[18:19], v[20:21], v[36:37]
	v_add_f32_e32 v20, v19, v38
	v_add_f32_e32 v20, v18, v20
	v_div_scale_f32 v21, s[4:5], v20, v20, 1.0
	v_rcp_f32_e32 v37, v21
	v_div_scale_f32 v36, vcc, 1.0, v20, 1.0
	v_fma_f32 v38, -v21, v37, 1.0
	v_fmac_f32_e32 v37, v38, v37
	v_mul_f32_e32 v38, v36, v37
	v_fma_f32 v39, -v21, v38, v36
	v_fmac_f32_e32 v38, v39, v37
	v_fma_f32 v21, -v21, v38, v36
	v_div_fmas_f32 v21, v21, v37, v38
	v_div_fixup_f32 v21, v21, v20, 1.0
	v_mul_f32_e32 v0, v0, v21
	v_mul_f32_e32 v20, v19, v21
	v_mul_f32_e32 v18, v18, v21
	v_lshlrev_b32_e32 v22, 16, v46
	v_and_b32_e32 v23, 0xffff0000, v46
	v_lshlrev_b32_e32 v6, 16, v47
	v_and_b32_e32 v7, 0xffff0000, v47
	v_lshlrev_b32_e32 v30, 16, v48
	v_and_b32_e32 v31, 0xffff0000, v48
	v_lshlrev_b32_e32 v8, 16, v49
	v_and_b32_e32 v9, 0xffff0000, v49
	v_lshlrev_b32_e32 v26, 16, v50
	v_and_b32_e32 v27, 0xffff0000, v50
	v_lshlrev_b32_e32 v10, 16, v51
	v_and_b32_e32 v11, 0xffff0000, v51
	v_lshlrev_b32_e32 v32, 16, v52
	v_and_b32_e32 v33, 0xffff0000, v52
	v_lshlrev_b32_e32 v12, 16, v53
	v_and_b32_e32 v13, 0xffff0000, v53
	v_pk_fma_f32 v[22:23], v[0:1], v[22:23], 0 op_sel_hi:[0,1,0]
	v_pk_fma_f32 v[6:7], v[0:1], v[6:7], 0 op_sel_hi:[0,1,0]
	v_pk_fma_f32 v[30:31], v[0:1], v[30:31], 0 op_sel_hi:[0,1,0]
	v_pk_fma_f32 v[8:9], v[0:1], v[8:9], 0 op_sel_hi:[0,1,0]
	v_lshlrev_b32_e32 v28, 16, v54
	v_and_b32_e32 v29, 0xffff0000, v54
	v_lshlrev_b32_e32 v14, 16, v55
	v_and_b32_e32 v15, 0xffff0000, v55
	v_lshlrev_b32_e32 v34, 16, v56
	v_and_b32_e32 v35, 0xffff0000, v56
	v_lshlrev_b32_e32 v16, 16, v57
	v_and_b32_e32 v17, 0xffff0000, v57
	v_pk_fma_f32 v[22:23], v[20:21], v[26:27], v[22:23] op_sel_hi:[0,1,1]
	v_pk_fma_f32 v[6:7], v[20:21], v[10:11], v[6:7] op_sel_hi:[0,1,1]
	v_pk_fma_f32 v[10:11], v[20:21], v[32:33], v[30:31] op_sel_hi:[0,1,1]
	v_pk_fma_f32 v[8:9], v[20:21], v[12:13], v[8:9] op_sel_hi:[0,1,1]
	v_pk_fma_f32 v[12:13], v[18:19], v[28:29], v[22:23] op_sel_hi:[0,1,1]
	v_pk_fma_f32 v[14:15], v[18:19], v[14:15], v[6:7] op_sel_hi:[0,1,1]
	v_pk_fma_f32 v[10:11], v[18:19], v[34:35], v[10:11] op_sel_hi:[0,1,1]
	v_pk_fma_f32 v[16:17], v[18:19], v[16:17], v[8:9] op_sel_hi:[0,1,1]
	v_cvt_pk_bf16_f32 v46, v12, v13
	v_cvt_pk_bf16_f32 v47, v14, v15
	v_cvt_pk_bf16_f32 v48, v10, v11
	v_cvt_pk_bf16_f32 v49, v16, v17
	global_store_dwordx4 v58, v[46:49], s[10:11]
	s_waitcnt vmcnt(37)
	v_max3_f32 v0, v64, v66, v68
	v_sub_f32_e32 v18, v64, v0
	v_sub_f32_e32 v36, v66, v0
	v_sub_f32_e32 v0, v68, v0
	v_cmp_gt_f32_e32 vcc, s19, v18
	v_cmp_gt_f32_e64 s[4:5], s19, v36
	v_cmp_gt_f32_e64 s[32:33], s19, v0
	v_cndmask_b32_e32 v37, 0, v4, vcc
	v_cndmask_b32_e64 v38, 0, v4, s[4:5]
	v_cndmask_b32_e64 v39, 0, v4, s[32:33]
	v_add_f32_e32 v18, v18, v37
	v_add_f32_e32 v36, v36, v38
	v_add_f32_e32 v0, v0, v39
	v_exp_f32_e32 v18, v18
	v_exp_f32_e32 v36, v36
	v_exp_f32_e32 v0, v0
	v_cndmask_b32_e32 v37, 0, v5, vcc
	v_cndmask_b32_e64 v38, 0, v5, s[4:5]
	v_cndmask_b32_e64 v39, 0, v5, s[32:33]
	v_mov_b32_e32 v20, v69
	v_mov_b32_e32 v21, v67
	v_ldexp_f32 v18, v18, v37
	v_ldexp_f32 v37, v36, v38
	v_ldexp_f32 v36, v0, v39
	v_mul_f32_e32 v0, v65, v18
	v_fma_f32 v38, v65, v18, 0
	v_pk_mul_f32 v[18:19], v[20:21], v[36:37]
	v_add_f32_e32 v20, v19, v38
	v_add_f32_e32 v20, v18, v20
	v_div_scale_f32 v21, s[4:5], v20, v20, 1.0
	v_rcp_f32_e32 v37, v21
	v_div_scale_f32 v36, vcc, 1.0, v20, 1.0
	v_fma_f32 v38, -v21, v37, 1.0
	v_fmac_f32_e32 v37, v38, v37
	v_mul_f32_e32 v38, v36, v37
	v_fma_f32 v39, -v21, v38, v36
	v_fmac_f32_e32 v38, v39, v37
	v_fma_f32 v21, -v21, v38, v36
	v_div_fmas_f32 v21, v21, v37, v38
	v_div_fixup_f32 v21, v21, v20, 1.0
	v_mul_f32_e32 v0, v0, v21
	v_mul_f32_e32 v20, v19, v21
	v_mul_f32_e32 v18, v18, v21
	v_lshlrev_b32_e32 v22, 16, v70
	v_and_b32_e32 v23, 0xffff0000, v70
	v_lshlrev_b32_e32 v6, 16, v71
	v_and_b32_e32 v7, 0xffff0000, v71
	v_lshlrev_b32_e32 v30, 16, v72
	v_and_b32_e32 v31, 0xffff0000, v72
	v_lshlrev_b32_e32 v8, 16, v73
	v_and_b32_e32 v9, 0xffff0000, v73
	v_lshlrev_b32_e32 v26, 16, v74
	v_and_b32_e32 v27, 0xffff0000, v74
	v_lshlrev_b32_e32 v10, 16, v75
	v_and_b32_e32 v11, 0xffff0000, v75
	v_lshlrev_b32_e32 v32, 16, v76
	v_and_b32_e32 v33, 0xffff0000, v76
	v_lshlrev_b32_e32 v12, 16, v77
	v_and_b32_e32 v13, 0xffff0000, v77
	v_pk_fma_f32 v[22:23], v[0:1], v[22:23], 0 op_sel_hi:[0,1,0]
	v_pk_fma_f32 v[6:7], v[0:1], v[6:7], 0 op_sel_hi:[0,1,0]
	v_pk_fma_f32 v[30:31], v[0:1], v[30:31], 0 op_sel_hi:[0,1,0]
	v_pk_fma_f32 v[8:9], v[0:1], v[8:9], 0 op_sel_hi:[0,1,0]
	v_lshlrev_b32_e32 v28, 16, v78
	v_and_b32_e32 v29, 0xffff0000, v78
	v_lshlrev_b32_e32 v14, 16, v79
	v_and_b32_e32 v15, 0xffff0000, v79
	v_lshlrev_b32_e32 v34, 16, v80
	v_and_b32_e32 v35, 0xffff0000, v80
	v_lshlrev_b32_e32 v16, 16, v81
	v_and_b32_e32 v17, 0xffff0000, v81
	v_pk_fma_f32 v[22:23], v[20:21], v[26:27], v[22:23] op_sel_hi:[0,1,1]
	v_pk_fma_f32 v[6:7], v[20:21], v[10:11], v[6:7] op_sel_hi:[0,1,1]
	v_pk_fma_f32 v[10:11], v[20:21], v[32:33], v[30:31] op_sel_hi:[0,1,1]
	v_pk_fma_f32 v[8:9], v[20:21], v[12:13], v[8:9] op_sel_hi:[0,1,1]
	v_pk_fma_f32 v[12:13], v[18:19], v[28:29], v[22:23] op_sel_hi:[0,1,1]
	v_pk_fma_f32 v[14:15], v[18:19], v[14:15], v[6:7] op_sel_hi:[0,1,1]
	v_pk_fma_f32 v[10:11], v[18:19], v[34:35], v[10:11] op_sel_hi:[0,1,1]
	v_pk_fma_f32 v[16:17], v[18:19], v[16:17], v[8:9] op_sel_hi:[0,1,1]
	v_cvt_pk_bf16_f32 v70, v12, v13
	v_cvt_pk_bf16_f32 v71, v14, v15
	v_cvt_pk_bf16_f32 v72, v10, v11
	v_cvt_pk_bf16_f32 v73, v16, v17
	global_store_dwordx4 v82, v[70:73], s[10:11]
	s_waitcnt vmcnt(32)
; __device__ __forceinline__ unsigned pk2(float lo, float hi) { f32x2_t v = {lo, hi}; bf16x2_t b = __builtin_convertvector(v, bf16x2_t); return __builtin_bit_cast(unsigned, b); }
; __device__ __forceinline__ float bflo(unsigned w) { return __uint_as_float(w << 16); }
; __device__ __forceinline__ float bfhi(unsigned w) { return __uint_as_float(w & 0xffff0000u); }
; __device__ __forceinline__ bf16* po_base(unsigned char* ws, int pat) { return (bf16*)(ws + (pat < 2 ? 436 * MiB + (size_t)pat * 32 * MiB : WS_Y)); }
; __device__ __forceinline__ void attn_combine(unsigned char* ws, const float* __restrict__ PM, bf16* CAT, int gtid, int gthreads, int iend = S * 128) {
;     ...
;         for (int p = 0; p < 3; ++p) { const f32x2_t ml = *(const f32x2_t*)(PM + (((size_t)p * S + t) * 8 + hh) * 2); mm[p] = ml[0]; ll[p] = ml[1]; }
;         const float ma = fmaxf(mm[0], fmaxf(mm[1], mm[2]));
;         float w[3], den = 0.f;
; #pragma unroll
;         for (int p = 0; p < 3; ++p) { w[p] = exp2f(mm[p] - ma) * ll[p]; den += w[p]; }
;         const float inv = 1.f / den;
;         float o[8] = {0.f, 0.f, 0.f, 0.f, 0.f, 0.f, 0.f, 0.f};
; #pragma unroll
;         for (int p = 0; p < 3; ++p) {
;             const u32x4 v = *(const u32x4*)(po_base(ws, p) + (size_t)t * 1024 + c); const float wp = w[p] * inv;
;             o[0] += wp * bflo(v.x); o[1] += wp * bfhi(v.x); o[2] += wp * bflo(v.y); o[3] += wp * bfhi(v.y); o[4] += wp * bflo(v.z); o[5] += wp * bfhi(v.z); o[6] += wp * bflo(v.w); o[7] += wp * bfhi(v.w);
;         }
;         u32x4 ov; ov.x = pk2(o[0], o[1]); ov.y = pk2(o[2], o[3]); ov.z = pk2(o[4], o[5]); ov.w = pk2(o[6], o[7]);
;         *(u32x4*)(CAT + (size_t)t * 2048 + c) = ov;
	v_max3_f32 v0, v88, v90, v92
	v_sub_f32_e32 v18, v88, v0
	v_sub_f32_e32 v36, v90, v0
	v_sub_f32_e32 v0, v92, v0
	v_cmp_gt_f32_e32 vcc, s19, v18
	v_cmp_gt_f32_e64 s[4:5], s19, v36
	v_cmp_gt_f32_e64 s[32:33], s19, v0
	v_cndmask_b32_e32 v37, 0, v4, vcc
	v_cndmask_b32_e64 v38, 0, v4, s[4:5]
	v_cndmask_b32_e64 v39, 0, v4, s[32:33]
	v_add_f32_e32 v18, v18, v37
	v_add_f32_e32 v36, v36, v38
	v_add_f32_e32 v0, v0, v39
	v_exp_f32_e32 v18, v18
	v_exp_f32_e32 v36, v36
	v_exp_f32_e32 v0, v0
	v_cndmask_b32_e32 v37, 0, v5, vcc
	v_cndmask_b32_e64 v38, 0, v5, s[4:5]
	v_cndmask_b32_e64 v39, 0, v5, s[32:33]
	v_mov_b32_e32 v20, v93
	v_mov_b32_e32 v21, v91
	v_ldexp_f32 v18, v18, v37
	v_ldexp_f32 v37, v36, v38
	v_ldexp_f32 v36, v0, v39
	v_mul_f32_e32 v0, v89, v18
	v_fma_f32 v38, v89, v18, 0
	v_pk_mul_f32 v[18:19], v[20:21], v[36:37]
	v_add_f32_e32 v20, v19, v38
	v_add_f32_e32 v20, v18, v20
	v_div_scale_f32 v21, s[4:5], v20, v20, 1.0
	v_rcp_f32_e32 v37, v21
	v_div_scale_f32 v36, vcc, 1.0, v20, 1.0
	v_fma_f32 v38, -v21, v37, 1.0
	v_fmac_f32_e32 v37, v38, v37
	v_mul_f32_e32 v38, v36, v37
	v_fma_f32 v39, -v21, v38, v36
	v_fmac_f32_e32 v38, v39, v37
	v_fma_f32 v21, -v21, v38, v36
	v_div_fmas_f32 v21, v21, v37, v38
	v_div_fixup_f32 v21, v21, v20, 1.0
	v_mul_f32_e32 v0, v0, v21
	v_mul_f32_e32 v20, v19, v21
	v_mul_f32_e32 v18, v18, v21
	v_lshlrev_b32_e32 v22, 16, v94
	v_and_b32_e32 v23, 0xffff0000, v94
	v_lshlrev_b32_e32 v6, 16, v95
	v_and_b32_e32 v7, 0xffff0000, v95
	v_lshlrev_b32_e32 v30, 16, v96
	v_and_b32_e32 v31, 0xffff0000, v96
	v_lshlrev_b32_e32 v8, 16, v97
	v_and_b32_e32 v9, 0xffff0000, v97
	v_lshlrev_b32_e32 v26, 16, v98
	v_and_b32_e32 v27, 0xffff0000, v98
	v_lshlrev_b32_e32 v10, 16, v99
	v_and_b32_e32 v11, 0xffff0000, v99
	v_lshlrev_b32_e32 v32, 16, v100
	v_and_b32_e32 v33, 0xffff0000, v100
	v_lshlrev_b32_e32 v12, 16, v101
	v_and_b32_e32 v13, 0xffff0000, v101
	v_pk_fma_f32 v[22:23], v[0:1], v[22:23], 0 op_sel_hi:[0,1,0]
	v_pk_fma_f32 v[6:7], v[0:1], v[6:7], 0 op_sel_hi:[0,1,0]
	v_pk_fma_f32 v[30:31], v[0:1], v[30:31], 0 op_sel_hi:[0,1,0]
	v_pk_fma_f32 v[8:9], v[0:1], v[8:9], 0 op_sel_hi:[0,1,0]
	v_lshlrev_b32_e32 v28, 16, v102
	v_and_b32_e32 v29, 0xffff0000, v102
	v_lshlrev_b32_e32 v14, 16, v103
	v_and_b32_e32 v15, 0xffff0000, v103
	v_lshlrev_b32_e32 v34, 16, v104
	v_and_b32_e32 v35, 0xffff0000, v104
	v_lshlrev_b32_e32 v16, 16, v105
	v_and_b32_e32 v17, 0xffff0000, v105
	v_pk_fma_f32 v[22:23], v[20:21], v[26:27], v[22:23] op_sel_hi:[0,1,1]
	v_pk_fma_f32 v[6:7], v[20:21], v[10:11], v[6:7] op_sel_hi:[0,1,1]
	v_pk_fma_f32 v[10:11], v[20:21], v[32:33], v[30:31] op_sel_hi:[0,1,1]
	v_pk_fma_f32 v[8:9], v[20:21], v[12:13], v[8:9] op_sel_hi:[0,1,1]
	v_pk_fma_f32 v[12:13], v[18:19], v[28:29], v[22:23] op_sel_hi:[0,1,1]
	v_pk_fma_f32 v[14:15], v[18:19], v[14:15], v[6:7] op_sel_hi:[0,1,1]
	v_pk_fma_f32 v[10:11], v[18:19], v[34:35], v[10:11] op_sel_hi:[0,1,1]
	v_pk_fma_f32 v[16:17], v[18:19], v[16:17], v[8:9] op_sel_hi:[0,1,1]
	v_cvt_pk_bf16_f32 v94, v12, v13
	v_cvt_pk_bf16_f32 v95, v14, v15
	v_cvt_pk_bf16_f32 v96, v10, v11
	v_cvt_pk_bf16_f32 v97, v16, v17
	global_store_dwordx4 v106, v[94:97], s[10:11]
	s_waitcnt vmcnt(27)
	v_max3_f32 v0, v112, v114, v116
	v_sub_f32_e32 v18, v112, v0
	v_sub_f32_e32 v36, v114, v0
	v_sub_f32_e32 v0, v116, v0
	v_cmp_gt_f32_e32 vcc, s19, v18
	v_cmp_gt_f32_e64 s[4:5], s19, v36
	v_cmp_gt_f32_e64 s[32:33], s19, v0
	v_cndmask_b32_e32 v37, 0, v4, vcc
	v_cndmask_b32_e64 v38, 0, v4, s[4:5]
	v_cndmask_b32_e64 v39, 0, v4, s[32:33]
	v_add_f32_e32 v18, v18, v37
	v_add_f32_e32 v36, v36, v38
	v_add_f32_e32 v0, v0, v39
	v_exp_f32_e32 v18, v18
	v_exp_f32_e32 v36, v36
	v_exp_f32_e32 v0, v0
	v_cndmask_b32_e32 v37, 0, v5, vcc
	v_cndmask_b32_e64 v38, 0, v5, s[4:5]
	v_cndmask_b32_e64 v39, 0, v5, s[32:33]
	v_mov_b32_e32 v20, v117
	v_mov_b32_e32 v21, v115
	v_ldexp_f32 v18, v18, v37
	v_ldexp_f32 v37, v36, v38
	v_ldexp_f32 v36, v0, v39
	v_mul_f32_e32 v0, v113, v18
	v_fma_f32 v38, v113, v18, 0
	v_pk_mul_f32 v[18:19], v[20:21], v[36:37]
	v_add_f32_e32 v20, v19, v38
	v_add_f32_e32 v20, v18, v20
	v_div_scale_f32 v21, s[4:5], v20, v20, 1.0
	v_rcp_f32_e32 v37, v21
	v_div_scale_f32 v36, vcc, 1.0, v20, 1.0
	v_fma_f32 v38, -v21, v37, 1.0
	v_fmac_f32_e32 v37, v38, v37
	v_mul_f32_e32 v38, v36, v37
	v_fma_f32 v39, -v21, v38, v36
	v_fmac_f32_e32 v38, v39, v37
	v_fma_f32 v21, -v21, v38, v36
	v_div_fmas_f32 v21, v21, v37, v38
	v_div_fixup_f32 v21, v21, v20, 1.0
	v_mul_f32_e32 v0, v0, v21
	v_mul_f32_e32 v20, v19, v21
	v_mul_f32_e32 v18, v18, v21
	v_lshlrev_b32_e32 v22, 16, v118
	v_and_b32_e32 v23, 0xffff0000, v118
	v_lshlrev_b32_e32 v6, 16, v119
	v_and_b32_e32 v7, 0xffff0000, v119
	v_lshlrev_b32_e32 v30, 16, v120
	v_and_b32_e32 v31, 0xffff0000, v120
	v_lshlrev_b32_e32 v8, 16, v121
	v_and_b32_e32 v9, 0xffff0000, v121
	v_lshlrev_b32_e32 v26, 16, v122
	v_and_b32_e32 v27, 0xffff0000, v122
	v_lshlrev_b32_e32 v10, 16, v123
	v_and_b32_e32 v11, 0xffff0000, v123
	v_lshlrev_b32_e32 v32, 16, v124
	v_and_b32_e32 v33, 0xffff0000, v124
	v_lshlrev_b32_e32 v12, 16, v125
	v_and_b32_e32 v13, 0xffff0000, v125
	v_pk_fma_f32 v[22:23], v[0:1], v[22:23], 0 op_sel_hi:[0,1,0]
	v_pk_fma_f32 v[6:7], v[0:1], v[6:7], 0 op_sel_hi:[0,1,0]
	v_pk_fma_f32 v[30:31], v[0:1], v[30:31], 0 op_sel_hi:[0,1,0]
	v_pk_fma_f32 v[8:9], v[0:1], v[8:9], 0 op_sel_hi:[0,1,0]
	v_lshlrev_b32_e32 v28, 16, v126
	v_and_b32_e32 v29, 0xffff0000, v126
	v_lshlrev_b32_e32 v14, 16, v127
	v_and_b32_e32 v15, 0xffff0000, v127
	v_lshlrev_b32_e32 v34, 16, v128
	v_and_b32_e32 v35, 0xffff0000, v128
	v_lshlrev_b32_e32 v16, 16, v129
	v_and_b32_e32 v17, 0xffff0000, v129
	v_pk_fma_f32 v[22:23], v[20:21], v[26:27], v[22:23] op_sel_hi:[0,1,1]
	v_pk_fma_f32 v[6:7], v[20:21], v[10:11], v[6:7] op_sel_hi:[0,1,1]
	v_pk_fma_f32 v[10:11], v[20:21], v[32:33], v[30:31] op_sel_hi:[0,1,1]
	v_pk_fma_f32 v[8:9], v[20:21], v[12:13], v[8:9] op_sel_hi:[0,1,1]
	v_pk_fma_f32 v[12:13], v[18:19], v[28:29], v[22:23] op_sel_hi:[0,1,1]
	v_pk_fma_f32 v[14:15], v[18:19], v[14:15], v[6:7] op_sel_hi:[0,1,1]
	v_pk_fma_f32 v[10:11], v[18:19], v[34:35], v[10:11] op_sel_hi:[0,1,1]
	v_pk_fma_f32 v[16:17], v[18:19], v[16:17], v[8:9] op_sel_hi:[0,1,1]
	v_cvt_pk_bf16_f32 v118, v12, v13
	v_cvt_pk_bf16_f32 v119, v14, v15
	v_cvt_pk_bf16_f32 v120, v10, v11
	v_cvt_pk_bf16_f32 v121, v16, v17
	global_store_dwordx4 v130, v[118:121], s[10:11]
	s_add_i32 s0, s0, -1
	s_cmp_eq_u32 s0, 1
	s_cbranch_scc1 .Lcmb_lastB
; __device__ __forceinline__ unsigned pk2(float lo, float hi) { f32x2_t v = {lo, hi}; bf16x2_t b = __builtin_convertvector(v, bf16x2_t); return __builtin_bit_cast(unsigned, b); }
; __device__ __forceinline__ float bflo(unsigned w) { return __uint_as_float(w << 16); }
; __device__ __forceinline__ float bfhi(unsigned w) { return __uint_as_float(w & 0xffff0000u); }
; __device__ __forceinline__ bf16* po_base(unsigned char* ws, int pat) { return (bf16*)(ws + (pat < 2 ? 436 * MiB + (size_t)pat * 32 * MiB : WS_Y)); }
; __device__ __forceinline__ void attn_combine(unsigned char* ws, const float* __restrict__ PM, bf16* CAT, int gtid, int gthreads, int iend = S * 128) {
;     for (int idx = gtid; idx < iend; idx += gthreads) {
;         const int t = idx >> 7, c = (idx & 127) * 8, hh = c >> 7;
;         float mm[3], ll[3];
; #pragma unroll
;         for (int p = 0; p < 3; ++p) { const f32x2_t ml = *(const f32x2_t*)(PM + (((size_t)p * S + t) * 8 + hh) * 2); mm[p] = ml[0]; ll[p] = ml[1]; }
;         const float ma = fmaxf(mm[0], fmaxf(mm[1], mm[2]));
;         float w[3], den = 0.f;
; #pragma unroll
;         for (int p = 0; p < 3; ++p) { w[p] = exp2f(mm[p] - ma) * ll[p]; den += w[p]; }
;         const float inv = 1.f / den;
;         float o[8] = {0.f, 0.f, 0.f, 0.f, 0.f, 0.f, 0.f, 0.f};
; #pragma unroll
;         for (int p = 0; p < 3; ++p) {
;             const u32x4 v = *(const u32x4*)(po_base(ws, p) + (size_t)t * 1024 + c); const float wp = w[p] * inv;
;             o[0] += wp * bflo(v.x); o[1] += wp * bfhi(v.x); o[2] += wp * bflo(v.y); o[3] += wp * bfhi(v.y); o[4] += wp * bflo(v.z); o[5] += wp * bfhi(v.z); o[6] += wp * bflo(v.w); o[7] += wp * bfhi(v.w);
;         }
;         u32x4 ov; ov.x = pk2(o[0], o[1]); ov.y = pk2(o[2], o[3]); ov.z = pk2(o[4], o[5]); ov.w = pk2(o[6], o[7]);
;         *(u32x4*)(CAT + (size_t)t * 2048 + c) = ov;
	v_min_i32_e32 v60, s1, v2
	v_ashrrev_i32_e32 v59, 7, v60
	v_lshrrev_b32_e32 v61, 1, v60
	v_and_b32_e32 v61, 56, v61
	v_lshl_or_b32 v61, v59, 6, v61
	global_load_dwordx2 v[40:41], v61, s[26:27]
	global_load_dwordx2 v[42:43], v61, s[6:7]
	global_load_dwordx2 v[44:45], v61, s[8:9]
	v_and_b32_e32 v58, 0x7f, v60
	v_lshlrev_b32_e32 v60, 4, v60
	v_lshlrev_b32_e32 v58, 4, v58
	global_load_dwordx4 v[46:49], v60, s[16:17] nt
	v_lshl_or_b32 v58, v59, 12, v58
	global_load_dwordx4 v[50:53], v60, s[20:21] nt
	global_load_dwordx4 v[54:57], v60, s[22:23] nt
	v_add_u32_e32 v84, 512, v2
	v_min_i32_e32 v84, s1, v84
	v_ashrrev_i32_e32 v83, 7, v84
	v_lshrrev_b32_e32 v85, 1, v84
	v_and_b32_e32 v85, 56, v85
	v_lshl_or_b32 v85, v83, 6, v85
	global_load_dwordx2 v[64:65], v85, s[26:27]
	global_load_dwordx2 v[66:67], v85, s[6:7]
	global_load_dwordx2 v[68:69], v85, s[8:9]
	v_and_b32_e32 v82, 0x7f, v84
	v_lshlrev_b32_e32 v84, 4, v84
	v_lshlrev_b32_e32 v82, 4, v82
	global_load_dwordx4 v[70:73], v84, s[16:17] nt
	v_lshl_or_b32 v82, v83, 12, v82
	global_load_dwordx4 v[74:77], v84, s[20:21] nt
	global_load_dwordx4 v[78:81], v84, s[22:23] nt
	v_add_u32_e32 v108, 1024, v2
	v_min_i32_e32 v108, s1, v108
	v_ashrrev_i32_e32 v107, 7, v108
	v_lshrrev_b32_e32 v109, 1, v108
	v_and_b32_e32 v109, 56, v109
	v_lshl_or_b32 v109, v107, 6, v109
	global_load_dwordx2 v[88:89], v109, s[26:27]
	global_load_dwordx2 v[90:91], v109, s[6:7]
	global_load_dwordx2 v[92:93], v109, s[8:9]
	v_and_b32_e32 v106, 0x7f, v108
	v_lshlrev_b32_e32 v108, 4, v108
	v_lshlrev_b32_e32 v106, 4, v106
	global_load_dwordx4 v[94:97], v108, s[16:17] nt
	v_lshl_or_b32 v106, v107, 12, v106
	global_load_dwordx4 v[98:101], v108, s[20:21] nt
	global_load_dwordx4 v[102:105], v108, s[22:23] nt
	v_add_u32_e32 v132, 1536, v2
	v_min_i32_e32 v132, s1, v132
	v_ashrrev_i32_e32 v131, 7, v132
	v_lshrrev_b32_e32 v133, 1, v132
	v_and_b32_e32 v133, 56, v133
	v_lshl_or_b32 v133, v131, 6, v133
	global_load_dwordx2 v[112:113], v133, s[26:27]
	global_load_dwordx2 v[114:115], v133, s[6:7]
	global_load_dwordx2 v[116:117], v133, s[8:9]
	v_and_b32_e32 v130, 0x7f, v132
	v_lshlrev_b32_e32 v132, 4, v132
	v_lshlrev_b32_e32 v130, 4, v130
	global_load_dwordx4 v[118:121], v132, s[16:17] nt
	v_lshl_or_b32 v130, v131, 12, v130
	global_load_dwordx4 v[122:125], v132, s[20:21] nt
	global_load_dwordx4 v[126:129], v132, s[22:23] nt
	v_add_u32_e32 v2, 2048, v2
	s_waitcnt vmcnt(42)
	v_max3_f32 v0, v136, v138, v140
	v_sub_f32_e32 v18, v136, v0
	v_sub_f32_e32 v36, v138, v0
	v_sub_f32_e32 v0, v140, v0
	v_cmp_gt_f32_e32 vcc, s19, v18
	v_cmp_gt_f32_e64 s[4:5], s19, v36
	v_cmp_gt_f32_e64 s[32:33], s19, v0
	v_cndmask_b32_e32 v37, 0, v4, vcc
	v_cndmask_b32_e64 v38, 0, v4, s[4:5]
	v_cndmask_b32_e64 v39, 0, v4, s[32:33]
	v_add_f32_e32 v18, v18, v37
	v_add_f32_e32 v36, v36, v38
	v_add_f32_e32 v0, v0, v39
	v_exp_f32_e32 v18, v18
	v_exp_f32_e32 v36, v36
	v_exp_f32_e32 v0, v0
	v_cndmask_b32_e32 v37, 0, v5, vcc
	v_cndmask_b32_e64 v38, 0, v5, s[4:5]
	v_cndmask_b32_e64 v39, 0, v5, s[32:33]
	v_mov_b32_e32 v20, v141
	v_mov_b32_e32 v21, v139
	v_ldexp_f32 v18, v18, v37
	v_ldexp_f32 v37, v36, v38
	v_ldexp_f32 v36, v0, v39
	v_mul_f32_e32 v0, v137, v18
	v_fma_f32 v38, v137, v18, 0
	v_pk_mul_f32 v[18:19], v[20:21], v[36:37]
	v_add_f32_e32 v20, v19, v38
	v_add_f32_e32 v20, v18, v20
	v_div_scale_f32 v21, s[4:5], v20, v20, 1.0
	v_rcp_f32_e32 v37, v21
	v_div_scale_f32 v36, vcc, 1.0, v20, 1.0
	v_fma_f32 v38, -v21, v37, 1.0
	v_fmac_f32_e32 v37, v38, v37
	v_mul_f32_e32 v38, v36, v37
	v_fma_f32 v39, -v21, v38, v36
	v_fmac_f32_e32 v38, v39, v37
	v_fma_f32 v21, -v21, v38, v36
	v_div_fmas_f32 v21, v21, v37, v38
	v_div_fixup_f32 v21, v21, v20, 1.0
	v_mul_f32_e32 v0, v0, v21
	v_mul_f32_e32 v20, v19, v21
	v_mul_f32_e32 v18, v18, v21
	v_lshlrev_b32_e32 v22, 16, v142
	v_and_b32_e32 v23, 0xffff0000, v142
	v_lshlrev_b32_e32 v6, 16, v143
	v_and_b32_e32 v7, 0xffff0000, v143
	v_lshlrev_b32_e32 v30, 16, v144
	v_and_b32_e32 v31, 0xffff0000, v144
	v_lshlrev_b32_e32 v8, 16, v145
	v_and_b32_e32 v9, 0xffff0000, v145
	v_lshlrev_b32_e32 v26, 16, v146
	v_and_b32_e32 v27, 0xffff0000, v146
	v_lshlrev_b32_e32 v10, 16, v147
	v_and_b32_e32 v11, 0xffff0000, v147
	v_lshlrev_b32_e32 v32, 16, v148
	v_and_b32_e32 v33, 0xffff0000, v148
	v_lshlrev_b32_e32 v12, 16, v149
	v_and_b32_e32 v13, 0xffff0000, v149
	v_pk_fma_f32 v[22:23], v[0:1], v[22:23], 0 op_sel_hi:[0,1,0]
	v_pk_fma_f32 v[6:7], v[0:1], v[6:7], 0 op_sel_hi:[0,1,0]
	v_pk_fma_f32 v[30:31], v[0:1], v[30:31], 0 op_sel_hi:[0,1,0]
	v_pk_fma_f32 v[8:9], v[0:1], v[8:9], 0 op_sel_hi:[0,1,0]
	v_lshlrev_b32_e32 v28, 16, v150
	v_and_b32_e32 v29, 0xffff0000, v150
	v_lshlrev_b32_e32 v14, 16, v151
	v_and_b32_e32 v15, 0xffff0000, v151
	v_lshlrev_b32_e32 v34, 16, v152
	v_and_b32_e32 v35, 0xffff0000, v152
	v_lshlrev_b32_e32 v16, 16, v153
	v_and_b32_e32 v17, 0xffff0000, v153
	v_pk_fma_f32 v[22:23], v[20:21], v[26:27], v[22:23] op_sel_hi:[0,1,1]
	v_pk_fma_f32 v[6:7], v[20:21], v[10:11], v[6:7] op_sel_hi:[0,1,1]
	v_pk_fma_f32 v[10:11], v[20:21], v[32:33], v[30:31] op_sel_hi:[0,1,1]
	v_pk_fma_f32 v[8:9], v[20:21], v[12:13], v[8:9] op_sel_hi:[0,1,1]
	v_pk_fma_f32 v[12:13], v[18:19], v[28:29], v[22:23] op_sel_hi:[0,1,1]
	v_pk_fma_f32 v[14:15], v[18:19], v[14:15], v[6:7] op_sel_hi:[0,1,1]
	v_pk_fma_f32 v[10:11], v[18:19], v[34:35], v[10:11] op_sel_hi:[0,1,1]
	v_pk_fma_f32 v[16:17], v[18:19], v[16:17], v[8:9] op_sel_hi:[0,1,1]
	v_cvt_pk_bf16_f32 v142, v12, v13
	v_cvt_pk_bf16_f32 v143, v14, v15
	v_cvt_pk_bf16_f32 v144, v10, v11
	v_cvt_pk_bf16_f32 v145, v16, v17
	global_store_dwordx4 v154, v[142:145], s[10:11]
	s_waitcnt vmcnt(37)
; __device__ __forceinline__ unsigned pk2(float lo, float hi) { f32x2_t v = {lo, hi}; bf16x2_t b = __builtin_convertvector(v, bf16x2_t); return __builtin_bit_cast(unsigned, b); }
; __device__ __forceinline__ float bflo(unsigned w) { return __uint_as_float(w << 16); }
; __device__ __forceinline__ float bfhi(unsigned w) { return __uint_as_float(w & 0xffff0000u); }
; __device__ __forceinline__ bf16* po_base(unsigned char* ws, int pat) { return (bf16*)(ws + (pat < 2 ? 436 * MiB + (size_t)pat * 32 * MiB : WS_Y)); }
; __device__ __forceinline__ void attn_combine(unsigned char* ws, const float* __restrict__ PM, bf16* CAT, int gtid, int gthreads, int iend = S * 128) {
;     ...
;         for (int p = 0; p < 3; ++p) { const f32x2_t ml = *(const f32x2_t*)(PM + (((size_t)p * S + t) * 8 + hh) * 2); mm[p] = ml[0]; ll[p] = ml[1]; }
;         const float ma = fmaxf(mm[0], fmaxf(mm[1], mm[2]));
;         float w[3], den = 0.f;
; #pragma unroll
;         for (int p = 0; p < 3; ++p) { w[p] = exp2f(mm[p] - ma) * ll[p]; den += w[p]; }
;         const float inv = 1.f / den;
;         float o[8] = {0.f, 0.f, 0.f, 0.f, 0.f, 0.f, 0.f, 0.f};
; #pragma unroll
;         for (int p = 0; p < 3; ++p) {
;             const u32x4 v = *(const u32x4*)(po_base(ws, p) + (size_t)t * 1024 + c); const float wp = w[p] * inv;
;             o[0] += wp * bflo(v.x); o[1] += wp * bfhi(v.x); o[2] += wp * bflo(v.y); o[3] += wp * bfhi(v.y); o[4] += wp * bflo(v.z); o[5] += wp * bfhi(v.z); o[6] += wp * bflo(v.w); o[7] += wp * bfhi(v.w);
;         }
;         u32x4 ov; ov.x = pk2(o[0], o[1]); ov.y = pk2(o[2], o[3]); ov.z = pk2(o[4], o[5]); ov.w = pk2(o[6], o[7]);
;         *(u32x4*)(CAT + (size_t)t * 2048 + c) = ov;
	v_max3_f32 v0, v160, v162, v164
	v_sub_f32_e32 v18, v160, v0
	v_sub_f32_e32 v36, v162, v0
	v_sub_f32_e32 v0, v164, v0
	v_cmp_gt_f32_e32 vcc, s19, v18
	v_cmp_gt_f32_e64 s[4:5], s19, v36
	v_cmp_gt_f32_e64 s[32:33], s19, v0
	v_cndmask_b32_e32 v37, 0, v4, vcc
	v_cndmask_b32_e64 v38, 0, v4, s[4:5]
	v_cndmask_b32_e64 v39, 0, v4, s[32:33]
	v_add_f32_e32 v18, v18, v37
	v_add_f32_e32 v36, v36, v38
	v_add_f32_e32 v0, v0, v39
	v_exp_f32_e32 v18, v18
	v_exp_f32_e32 v36, v36
	v_exp_f32_e32 v0, v0
	v_cndmask_b32_e32 v37, 0, v5, vcc
	v_cndmask_b32_e64 v38, 0, v5, s[4:5]
	v_cndmask_b32_e64 v39, 0, v5, s[32:33]
	v_mov_b32_e32 v20, v165
	v_mov_b32_e32 v21, v163
	v_ldexp_f32 v18, v18, v37
	v_ldexp_f32 v37, v36, v38
	v_ldexp_f32 v36, v0, v39
	v_mul_f32_e32 v0, v161, v18
	v_fma_f32 v38, v161, v18, 0
	v_pk_mul_f32 v[18:19], v[20:21], v[36:37]
	v_add_f32_e32 v20, v19, v38
	v_add_f32_e32 v20, v18, v20
	v_div_scale_f32 v21, s[4:5], v20, v20, 1.0
	v_rcp_f32_e32 v37, v21
	v_div_scale_f32 v36, vcc, 1.0, v20, 1.0
	v_fma_f32 v38, -v21, v37, 1.0
	v_fmac_f32_e32 v37, v38, v37
	v_mul_f32_e32 v38, v36, v37
	v_fma_f32 v39, -v21, v38, v36
	v_fmac_f32_e32 v38, v39, v37
	v_fma_f32 v21, -v21, v38, v36
	v_div_fmas_f32 v21, v21, v37, v38
	v_div_fixup_f32 v21, v21, v20, 1.0
	v_mul_f32_e32 v0, v0, v21
	v_mul_f32_e32 v20, v19, v21
	v_mul_f32_e32 v18, v18, v21
	v_lshlrev_b32_e32 v22, 16, v166
	v_and_b32_e32 v23, 0xffff0000, v166
	v_lshlrev_b32_e32 v6, 16, v167
	v_and_b32_e32 v7, 0xffff0000, v167
	v_lshlrev_b32_e32 v30, 16, v168
	v_and_b32_e32 v31, 0xffff0000, v168
	v_lshlrev_b32_e32 v8, 16, v169
	v_and_b32_e32 v9, 0xffff0000, v169
	v_lshlrev_b32_e32 v26, 16, v170
	v_and_b32_e32 v27, 0xffff0000, v170
	v_lshlrev_b32_e32 v10, 16, v171
	v_and_b32_e32 v11, 0xffff0000, v171
	v_lshlrev_b32_e32 v32, 16, v172
	v_and_b32_e32 v33, 0xffff0000, v172
	v_lshlrev_b32_e32 v12, 16, v173
	v_and_b32_e32 v13, 0xffff0000, v173
	v_pk_fma_f32 v[22:23], v[0:1], v[22:23], 0 op_sel_hi:[0,1,0]
	v_pk_fma_f32 v[6:7], v[0:1], v[6:7], 0 op_sel_hi:[0,1,0]
	v_pk_fma_f32 v[30:31], v[0:1], v[30:31], 0 op_sel_hi:[0,1,0]
	v_pk_fma_f32 v[8:9], v[0:1], v[8:9], 0 op_sel_hi:[0,1,0]
	v_lshlrev_b32_e32 v28, 16, v174
	v_and_b32_e32 v29, 0xffff0000, v174
	v_lshlrev_b32_e32 v14, 16, v175
	v_and_b32_e32 v15, 0xffff0000, v175
	v_lshlrev_b32_e32 v34, 16, v176
	v_and_b32_e32 v35, 0xffff0000, v176
	v_lshlrev_b32_e32 v16, 16, v177
	v_and_b32_e32 v17, 0xffff0000, v177
	v_pk_fma_f32 v[22:23], v[20:21], v[26:27], v[22:23] op_sel_hi:[0,1,1]
	v_pk_fma_f32 v[6:7], v[20:21], v[10:11], v[6:7] op_sel_hi:[0,1,1]
	v_pk_fma_f32 v[10:11], v[20:21], v[32:33], v[30:31] op_sel_hi:[0,1,1]
	v_pk_fma_f32 v[8:9], v[20:21], v[12:13], v[8:9] op_sel_hi:[0,1,1]
	v_pk_fma_f32 v[12:13], v[18:19], v[28:29], v[22:23] op_sel_hi:[0,1,1]
	v_pk_fma_f32 v[14:15], v[18:19], v[14:15], v[6:7] op_sel_hi:[0,1,1]
	v_pk_fma_f32 v[10:11], v[18:19], v[34:35], v[10:11] op_sel_hi:[0,1,1]
	v_pk_fma_f32 v[16:17], v[18:19], v[16:17], v[8:9] op_sel_hi:[0,1,1]
	v_cvt_pk_bf16_f32 v166, v12, v13
	v_cvt_pk_bf16_f32 v167, v14, v15
	v_cvt_pk_bf16_f32 v168, v10, v11
	v_cvt_pk_bf16_f32 v169, v16, v17
	global_store_dwordx4 v178, v[166:169], s[10:11]
	s_waitcnt vmcnt(32)
	v_max3_f32 v0, v188, v190, v192
	v_sub_f32_e32 v18, v188, v0
	v_sub_f32_e32 v36, v190, v0
	v_sub_f32_e32 v0, v192, v0
	v_cmp_gt_f32_e32 vcc, s19, v18
	v_cmp_gt_f32_e64 s[4:5], s19, v36
	v_cmp_gt_f32_e64 s[32:33], s19, v0
	v_cndmask_b32_e32 v37, 0, v4, vcc
	v_cndmask_b32_e64 v38, 0, v4, s[4:5]
	v_cndmask_b32_e64 v39, 0, v4, s[32:33]
	v_add_f32_e32 v18, v18, v37
	v_add_f32_e32 v36, v36, v38
	v_add_f32_e32 v0, v0, v39
	v_exp_f32_e32 v18, v18
	v_exp_f32_e32 v36, v36
	v_exp_f32_e32 v0, v0
	v_cndmask_b32_e32 v37, 0, v5, vcc
	v_cndmask_b32_e64 v38, 0, v5, s[4:5]
	v_cndmask_b32_e64 v39, 0, v5, s[32:33]
	v_mov_b32_e32 v20, v193
	v_mov_b32_e32 v21, v191
	v_ldexp_f32 v18, v18, v37
	v_ldexp_f32 v37, v36, v38
	v_ldexp_f32 v36, v0, v39
	v_mul_f32_e32 v0, v189, v18
	v_fma_f32 v38, v189, v18, 0
	v_pk_mul_f32 v[18:19], v[20:21], v[36:37]
	v_add_f32_e32 v20, v19, v38
	v_add_f32_e32 v20, v18, v20
	v_div_scale_f32 v21, s[4:5], v20, v20, 1.0
	v_rcp_f32_e32 v37, v21
	v_div_scale_f32 v36, vcc, 1.0, v20, 1.0
	v_fma_f32 v38, -v21, v37, 1.0
	v_fmac_f32_e32 v37, v38, v37
	v_mul_f32_e32 v38, v36, v37
	v_fma_f32 v39, -v21, v38, v36
	v_fmac_f32_e32 v38, v39, v37
	v_fma_f32 v21, -v21, v38, v36
	v_div_fmas_f32 v21, v21, v37, v38
	v_div_fixup_f32 v21, v21, v20, 1.0
	v_mul_f32_e32 v0, v0, v21
	v_mul_f32_e32 v20, v19, v21
	v_mul_f32_e32 v18, v18, v21
	v_lshlrev_b32_e32 v22, 16, v194
	v_and_b32_e32 v23, 0xffff0000, v194
	v_lshlrev_b32_e32 v6, 16, v195
	v_and_b32_e32 v7, 0xffff0000, v195
	v_lshlrev_b32_e32 v30, 16, v196
	v_and_b32_e32 v31, 0xffff0000, v196
	v_lshlrev_b32_e32 v8, 16, v197
	v_and_b32_e32 v9, 0xffff0000, v197
	v_lshlrev_b32_e32 v26, 16, v198
	v_and_b32_e32 v27, 0xffff0000, v198
	v_lshlrev_b32_e32 v10, 16, v199
	v_and_b32_e32 v11, 0xffff0000, v199
	v_lshlrev_b32_e32 v32, 16, v200
	v_and_b32_e32 v33, 0xffff0000, v200
	v_lshlrev_b32_e32 v12, 16, v201
	v_and_b32_e32 v13, 0xffff0000, v201
	v_pk_fma_f32 v[22:23], v[0:1], v[22:23], 0 op_sel_hi:[0,1,0]
	v_pk_fma_f32 v[6:7], v[0:1], v[6:7], 0 op_sel_hi:[0,1,0]
	v_pk_fma_f32 v[30:31], v[0:1], v[30:31], 0 op_sel_hi:[0,1,0]
	v_pk_fma_f32 v[8:9], v[0:1], v[8:9], 0 op_sel_hi:[0,1,0]
	v_lshlrev_b32_e32 v28, 16, v202
	v_and_b32_e32 v29, 0xffff0000, v202
	v_lshlrev_b32_e32 v14, 16, v203
	v_and_b32_e32 v15, 0xffff0000, v203
	v_lshlrev_b32_e32 v34, 16, v204
	v_and_b32_e32 v35, 0xffff0000, v204
	v_lshlrev_b32_e32 v16, 16, v205
	v_and_b32_e32 v17, 0xffff0000, v205
	v_pk_fma_f32 v[22:23], v[20:21], v[26:27], v[22:23] op_sel_hi:[0,1,1]
	v_pk_fma_f32 v[6:7], v[20:21], v[10:11], v[6:7] op_sel_hi:[0,1,1]
	v_pk_fma_f32 v[10:11], v[20:21], v[32:33], v[30:31] op_sel_hi:[0,1,1]
	v_pk_fma_f32 v[8:9], v[20:21], v[12:13], v[8:9] op_sel_hi:[0,1,1]
	v_pk_fma_f32 v[12:13], v[18:19], v[28:29], v[22:23] op_sel_hi:[0,1,1]
	v_pk_fma_f32 v[14:15], v[18:19], v[14:15], v[6:7] op_sel_hi:[0,1,1]
	v_pk_fma_f32 v[10:11], v[18:19], v[34:35], v[10:11] op_sel_hi:[0,1,1]
	v_pk_fma_f32 v[16:17], v[18:19], v[16:17], v[8:9] op_sel_hi:[0,1,1]
	v_cvt_pk_bf16_f32 v194, v12, v13
	v_cvt_pk_bf16_f32 v195, v14, v15
	v_cvt_pk_bf16_f32 v196, v10, v11
	v_cvt_pk_bf16_f32 v197, v16, v17
	global_store_dwordx4 v206, v[194:197], s[10:11]
	s_waitcnt vmcnt(27)
; __device__ __forceinline__ unsigned pk2(float lo, float hi) { f32x2_t v = {lo, hi}; bf16x2_t b = __builtin_convertvector(v, bf16x2_t); return __builtin_bit_cast(unsigned, b); }
; __device__ __forceinline__ float bflo(unsigned w) { return __uint_as_float(w << 16); }
; __device__ __forceinline__ float bfhi(unsigned w) { return __uint_as_float(w & 0xffff0000u); }
; __device__ __forceinline__ bf16* po_base(unsigned char* ws, int pat) { return (bf16*)(ws + (pat < 2 ? 436 * MiB + (size_t)pat * 32 * MiB : WS_Y)); }
; __device__ __forceinline__ void attn_combine(unsigned char* ws, const float* __restrict__ PM, bf16* CAT, int gtid, int gthreads, int iend = S * 128) {
;     ...
;         for (int p = 0; p < 3; ++p) { const f32x2_t ml = *(const f32x2_t*)(PM + (((size_t)p * S + t) * 8 + hh) * 2); mm[p] = ml[0]; ll[p] = ml[1]; }
;         const float ma = fmaxf(mm[0], fmaxf(mm[1], mm[2]));
;         float w[3], den = 0.f;
; #pragma unroll
;         for (int p = 0; p < 3; ++p) { w[p] = exp2f(mm[p] - ma) * ll[p]; den += w[p]; }
;         const float inv = 1.f / den;
;         float o[8] = {0.f, 0.f, 0.f, 0.f, 0.f, 0.f, 0.f, 0.f};
; #pragma unroll
;         for (int p = 0; p < 3; ++p) {
;             const u32x4 v = *(const u32x4*)(po_base(ws, p) + (size_t)t * 1024 + c); const float wp = w[p] * inv;
;             o[0] += wp * bflo(v.x); o[1] += wp * bfhi(v.x); o[2] += wp * bflo(v.y); o[3] += wp * bfhi(v.y); o[4] += wp * bflo(v.z); o[5] += wp * bfhi(v.z); o[6] += wp * bflo(v.w); o[7] += wp * bfhi(v.w);
;         }
;         u32x4 ov; ov.x = pk2(o[0], o[1]); ov.y = pk2(o[2], o[3]); ov.z = pk2(o[4], o[5]); ov.w = pk2(o[6], o[7]);
;         *(u32x4*)(CAT + (size_t)t * 2048 + c) = ov;
	v_max3_f32 v0, v212, v214, v216
	v_sub_f32_e32 v18, v212, v0
	v_sub_f32_e32 v36, v214, v0
	v_sub_f32_e32 v0, v216, v0
	v_cmp_gt_f32_e32 vcc, s19, v18
	v_cmp_gt_f32_e64 s[4:5], s19, v36
	v_cmp_gt_f32_e64 s[32:33], s19, v0
	v_cndmask_b32_e32 v37, 0, v4, vcc
	v_cndmask_b32_e64 v38, 0, v4, s[4:5]
	v_cndmask_b32_e64 v39, 0, v4, s[32:33]
	v_add_f32_e32 v18, v18, v37
	v_add_f32_e32 v36, v36, v38
	v_add_f32_e32 v0, v0, v39
	v_exp_f32_e32 v18, v18
	v_exp_f32_e32 v36, v36
	v_exp_f32_e32 v0, v0
	v_cndmask_b32_e32 v37, 0, v5, vcc
	v_cndmask_b32_e64 v38, 0, v5, s[4:5]
	v_cndmask_b32_e64 v39, 0, v5, s[32:33]
	v_mov_b32_e32 v20, v217
	v_mov_b32_e32 v21, v215
	v_ldexp_f32 v18, v18, v37
	v_ldexp_f32 v37, v36, v38
	v_ldexp_f32 v36, v0, v39
	v_mul_f32_e32 v0, v213, v18
	v_fma_f32 v38, v213, v18, 0
	v_pk_mul_f32 v[18:19], v[20:21], v[36:37]
	v_add_f32_e32 v20, v19, v38
	v_add_f32_e32 v20, v18, v20
	v_div_scale_f32 v21, s[4:5], v20, v20, 1.0
	v_rcp_f32_e32 v37, v21
	v_div_scale_f32 v36, vcc, 1.0, v20, 1.0
	v_fma_f32 v38, -v21, v37, 1.0
	v_fmac_f32_e32 v37, v38, v37
	v_mul_f32_e32 v38, v36, v37
	v_fma_f32 v39, -v21, v38, v36
	v_fmac_f32_e32 v38, v39, v37
	v_fma_f32 v21, -v21, v38, v36
	v_div_fmas_f32 v21, v21, v37, v38
	v_div_fixup_f32 v21, v21, v20, 1.0
	v_mul_f32_e32 v0, v0, v21
	v_mul_f32_e32 v20, v19, v21
	v_mul_f32_e32 v18, v18, v21
	v_lshlrev_b32_e32 v22, 16, v218
	v_and_b32_e32 v23, 0xffff0000, v218
	v_lshlrev_b32_e32 v6, 16, v219
	v_and_b32_e32 v7, 0xffff0000, v219
	v_lshlrev_b32_e32 v30, 16, v220
	v_and_b32_e32 v31, 0xffff0000, v220
	v_lshlrev_b32_e32 v8, 16, v221
	v_and_b32_e32 v9, 0xffff0000, v221
	v_lshlrev_b32_e32 v26, 16, v222
	v_and_b32_e32 v27, 0xffff0000, v222
	v_lshlrev_b32_e32 v10, 16, v223
	v_and_b32_e32 v11, 0xffff0000, v223
	v_lshlrev_b32_e32 v32, 16, v224
	v_and_b32_e32 v33, 0xffff0000, v224
	v_lshlrev_b32_e32 v12, 16, v225
	v_and_b32_e32 v13, 0xffff0000, v225
	v_pk_fma_f32 v[22:23], v[0:1], v[22:23], 0 op_sel_hi:[0,1,0]
	v_pk_fma_f32 v[6:7], v[0:1], v[6:7], 0 op_sel_hi:[0,1,0]
	v_pk_fma_f32 v[30:31], v[0:1], v[30:31], 0 op_sel_hi:[0,1,0]
	v_pk_fma_f32 v[8:9], v[0:1], v[8:9], 0 op_sel_hi:[0,1,0]
	v_lshlrev_b32_e32 v28, 16, v226
	v_and_b32_e32 v29, 0xffff0000, v226
	v_lshlrev_b32_e32 v14, 16, v227
	v_and_b32_e32 v15, 0xffff0000, v227
	v_lshlrev_b32_e32 v34, 16, v228
	v_and_b32_e32 v35, 0xffff0000, v228
	v_lshlrev_b32_e32 v16, 16, v229
	v_and_b32_e32 v17, 0xffff0000, v229
	v_pk_fma_f32 v[22:23], v[20:21], v[26:27], v[22:23] op_sel_hi:[0,1,1]
	v_pk_fma_f32 v[6:7], v[20:21], v[10:11], v[6:7] op_sel_hi:[0,1,1]
	v_pk_fma_f32 v[10:11], v[20:21], v[32:33], v[30:31] op_sel_hi:[0,1,1]
	v_pk_fma_f32 v[8:9], v[20:21], v[12:13], v[8:9] op_sel_hi:[0,1,1]
	v_pk_fma_f32 v[12:13], v[18:19], v[28:29], v[22:23] op_sel_hi:[0,1,1]
	v_pk_fma_f32 v[14:15], v[18:19], v[14:15], v[6:7] op_sel_hi:[0,1,1]
	v_pk_fma_f32 v[10:11], v[18:19], v[34:35], v[10:11] op_sel_hi:[0,1,1]
	v_pk_fma_f32 v[16:17], v[18:19], v[16:17], v[8:9] op_sel_hi:[0,1,1]
	v_cvt_pk_bf16_f32 v218, v12, v13
	v_cvt_pk_bf16_f32 v219, v14, v15
	v_cvt_pk_bf16_f32 v220, v10, v11
	v_cvt_pk_bf16_f32 v221, v16, v17
	global_store_dwordx4 v230, v[218:221], s[10:11]
	s_add_i32 s0, s0, -1
	s_branch .Lcmb_loop
